# short-conv unit: four items (28 loads) in flight per trip instead of two
# speedup vs baseline: 1.0037x; 1.0000x over previous
; __device__ __forceinline__ size_t paddr(int row, int col) { return ((size_t)(col >> 7) * 16384 + (size_t)row) * 128 + (col & 127); }
;     __device__ __forceinline__ const float* in(int i) const { return (const float*)(const __attribute__((address_space(1))) float*)ld(i); }
; __device__ __forceinline__ void mixers_phase(const PP& p, int l, int hf, unsigned char* lds) {
;     ...
;         {
;             const float* cw = p.in(I_CONVW) + (size_t)l * 3 * 1024;
;             const int i0 = (unit - 512) * 8192 + tid;
; #pragma unroll 2
;             for (int k = 0; k < 16; ++k) {
;                 const int i = i0 + k * 512;
;                 const int row = i >> 7, c8 = (i & 127) * 8, t = row & (SEQ - 1);
;                 const bf16* src = proj + paddr(row, c8);
;                 constexpr size_t SEGS = (size_t)8 * TH * 128;
;                 float cb[8], a[8], bq[8], acc[8];
;                 unpk8(*(const u32x4*)(src), cb);
;                 unpk8(*(const u32x4*)(src + SEGS), a); unpk8(*(const u32x4*)(src + 2 * SEGS), bq);
;                 const f32x4 w2a = *(const f32x4*)(cw + 2048 + c8), w2b = *(const f32x4*)(cw + 2048 + c8 + 4);
; #pragma unroll
;                 for (int j = 0; j < 8; ++j) acc[j] = (j < 4 ? w2a[j] : w2b[j - 4]) * a[j] * bq[j];
;                 if (t >= 1) {
;                     unpk8(*(const u32x4*)(src - 128 + SEGS), a); unpk8(*(const u32x4*)(src - 128 + 2 * SEGS), bq);
;                     const f32x4 w1a = *(const f32x4*)(cw + 1024 + c8), w1b = *(const f32x4*)(cw + 1024 + c8 + 4);
; #pragma unroll
;                     for (int j = 0; j < 8; ++j) acc[j] += (j < 4 ? w1a[j] : w1b[j - 4]) * a[j] * bq[j];
;                 }
;                 if (t >= 2) {
;                     unpk8(*(const u32x4*)(src - 256 + SEGS), a); unpk8(*(const u32x4*)(src - 256 + 2 * SEGS), bq);
;                     const f32x4 w0a = *(const f32x4*)(cw + c8), w0b = *(const f32x4*)(cw + c8 + 4);
; #pragma unroll
;                     for (int j = 0; j < 8; ++j) acc[j] += (j < 4 ? w0a[j] : w0b[j - 4]) * a[j] * bq[j];
;                 }
;                 u32x4 o; o.x = pk2(cb[0] * acc[0], cb[1] * acc[1]); o.y = pk2(cb[2] * acc[2], cb[3] * acc[3]); o.z = pk2(cb[4] * acc[4], cb[5] * acc[5]); o.w = pk2(cb[6] * acc[6], cb[7] * acc[7]);
;                 *(u32x4*)(Y + (size_t)row * 1024 + c8) = o;
;             }
.LBB0_270:
	v_add_u32_e32 v23, s2, v22
	v_add_u32_e32 v0, 0xffc02000, v23
	v_ashrrev_i32_e32 v10, 7, v0
	v_ashrrev_i32_e32 v11, 31, v10
	v_lshlrev_b64 v[0:1], 8, v[10:11]
	v_lshl_add_u64 v[20:21], v[144:145], 0, v[0:1]
	v_lshl_add_u64 v[46:47], v[20:21], 0, s[8:9]
	v_lshl_add_u64 v[48:49], v[20:21], 0, s[16:17]
	global_load_dwordx4 v[50:53], v[20:21], off
	global_load_dwordx4 v[54:57], v[46:47], off
	global_load_dwordx4 v[58:61], v[48:49], off
	global_load_dwordx4 v[62:65], v[46:47], off offset:-256
	global_load_dwordx4 v[66:69], v[48:49], off offset:-256
	global_load_dwordx4 v[70:73], v[46:47], off offset:-512
	global_load_dwordx4 v[74:77], v[48:49], off offset:-512
	global_load_dwordx4 v[78:81], v[20:21], off offset:1024
	global_load_dwordx4 v[82:85], v[46:47], off offset:1024
	global_load_dwordx4 v[86:89], v[48:49], off offset:1024
	global_load_dwordx4 v[90:93], v[46:47], off offset:768
	global_load_dwordx4 v[94:97], v[48:49], off offset:768
	global_load_dwordx4 v[98:101], v[46:47], off offset:512
	global_load_dwordx4 v[102:105], v[48:49], off offset:512
	global_load_dwordx4 v[156:159], v[20:21], off offset:2048
	global_load_dwordx4 v[160:163], v[46:47], off offset:2048
	global_load_dwordx4 v[164:167], v[48:49], off offset:2048
	global_load_dwordx4 v[168:171], v[46:47], off offset:1792
	global_load_dwordx4 v[172:175], v[48:49], off offset:1792
	global_load_dwordx4 v[176:179], v[46:47], off offset:1536
	global_load_dwordx4 v[180:183], v[48:49], off offset:1536
	global_load_dwordx4 v[184:187], v[20:21], off offset:3072
	global_load_dwordx4 v[198:201], v[46:47], off offset:3072
	global_load_dwordx4 v[202:205], v[48:49], off offset:3072
	global_load_dwordx4 v[206:209], v[46:47], off offset:2816
	global_load_dwordx4 v[210:213], v[48:49], off offset:2816
	global_load_dwordx4 v[214:217], v[46:47], off offset:2560
	global_load_dwordx4 v[218:221], v[48:49], off offset:2560
	v_and_b32_e32 v38, 0x7ff, v10
	v_add_u32_e32 v39, 4, v10
	v_and_b32_e32 v39, 0x7ff, v39
	v_add_u32_e32 v44, 8, v10
	v_and_b32_e32 v44, 0x7ff, v44
	v_add_u32_e32 v45, 12, v10
	v_and_b32_e32 v45, 0x7ff, v45
	v_lshlrev_b64 v[10:11], 11, v[10:11]
	v_lshl_add_u64 v[130:131], v[146:147], 0, v[10:11]
	v_lshl_add_u64 v[132:133], v[130:131], 0, s[18:19]
	v_lshl_add_u64 v[134:135], v[132:133], 0, s[18:19]
	v_lshl_add_u64 v[136:137], v[134:135], 0, s[18:19]
	s_waitcnt vmcnt(21)
	v_lshlrev_b32_e32 v32, 16, v54
	v_and_b32_e32 v33, 0xffff0000, v54
	v_lshlrev_b32_e32 v34, 16, v58
	v_and_b32_e32 v35, 0xffff0000, v58
	v_pk_mul_f32 v[24:25], v[106:107], v[32:33]
	v_pk_mul_f32 v[24:25], v[24:25], v[34:35]
	v_lshlrev_b32_e32 v32, 16, v55
	v_and_b32_e32 v33, 0xffff0000, v55
	v_lshlrev_b32_e32 v34, 16, v59
	v_and_b32_e32 v35, 0xffff0000, v59
	v_pk_mul_f32 v[26:27], v[108:109], v[32:33]
	v_pk_mul_f32 v[26:27], v[26:27], v[34:35]
	v_lshlrev_b32_e32 v32, 16, v56
	v_and_b32_e32 v33, 0xffff0000, v56
	v_lshlrev_b32_e32 v34, 16, v60
	v_and_b32_e32 v35, 0xffff0000, v60
	v_pk_mul_f32 v[28:29], v[110:111], v[32:33]
	v_pk_mul_f32 v[28:29], v[28:29], v[34:35]
	v_lshlrev_b32_e32 v32, 16, v57
	v_and_b32_e32 v33, 0xffff0000, v57
	v_lshlrev_b32_e32 v34, 16, v61
	v_and_b32_e32 v35, 0xffff0000, v61
	v_pk_mul_f32 v[30:31], v[112:113], v[32:33]
	v_pk_mul_f32 v[30:31], v[30:31], v[34:35]
	v_cmp_ne_u32_e32 vcc, 0, v38
	s_and_saveexec_b64 s[6:7], vcc
	v_lshlrev_b32_e32 v32, 16, v62
	v_and_b32_e32 v33, 0xffff0000, v62
	v_lshlrev_b32_e32 v34, 16, v66
	v_and_b32_e32 v35, 0xffff0000, v66
	v_pk_mul_f32 v[36:37], v[114:115], v[32:33]
	v_pk_fma_f32 v[24:25], v[36:37], v[34:35], v[24:25]
	v_lshlrev_b32_e32 v32, 16, v63
	v_and_b32_e32 v33, 0xffff0000, v63
	v_lshlrev_b32_e32 v34, 16, v67
	v_and_b32_e32 v35, 0xffff0000, v67
	v_pk_mul_f32 v[36:37], v[116:117], v[32:33]
	v_pk_fma_f32 v[26:27], v[36:37], v[34:35], v[26:27]
	v_lshlrev_b32_e32 v32, 16, v64
	v_and_b32_e32 v33, 0xffff0000, v64
	v_lshlrev_b32_e32 v34, 16, v68
	v_and_b32_e32 v35, 0xffff0000, v68
	v_pk_mul_f32 v[36:37], v[118:119], v[32:33]
	v_pk_fma_f32 v[28:29], v[36:37], v[34:35], v[28:29]
	v_lshlrev_b32_e32 v32, 16, v65
	v_and_b32_e32 v33, 0xffff0000, v65
	v_lshlrev_b32_e32 v34, 16, v69
	v_and_b32_e32 v35, 0xffff0000, v69
	v_pk_mul_f32 v[36:37], v[120:121], v[32:33]
	v_pk_fma_f32 v[30:31], v[36:37], v[34:35], v[30:31]
	s_or_b64 exec, exec, s[6:7]
	v_cmp_lt_u32_e32 vcc, 1, v38
	s_and_saveexec_b64 s[6:7], vcc
	v_lshlrev_b32_e32 v32, 16, v70
	v_and_b32_e32 v33, 0xffff0000, v70
	v_lshlrev_b32_e32 v34, 16, v74
	v_and_b32_e32 v35, 0xffff0000, v74
	v_pk_mul_f32 v[36:37], v[122:123], v[32:33]
	v_pk_fma_f32 v[24:25], v[36:37], v[34:35], v[24:25]
	v_lshlrev_b32_e32 v32, 16, v71
	v_and_b32_e32 v33, 0xffff0000, v71
	v_lshlrev_b32_e32 v34, 16, v75
	v_and_b32_e32 v35, 0xffff0000, v75
	v_pk_mul_f32 v[36:37], v[124:125], v[32:33]
	v_pk_fma_f32 v[26:27], v[36:37], v[34:35], v[26:27]
	v_lshlrev_b32_e32 v32, 16, v72
	v_and_b32_e32 v33, 0xffff0000, v72
	v_lshlrev_b32_e32 v34, 16, v76
	v_and_b32_e32 v35, 0xffff0000, v76
	v_pk_mul_f32 v[36:37], v[126:127], v[32:33]
	v_pk_fma_f32 v[28:29], v[36:37], v[34:35], v[28:29]
	v_lshlrev_b32_e32 v32, 16, v73
	v_and_b32_e32 v33, 0xffff0000, v73
	v_lshlrev_b32_e32 v34, 16, v77
	v_and_b32_e32 v35, 0xffff0000, v77
	v_pk_mul_f32 v[36:37], v[128:129], v[32:33]
	v_pk_fma_f32 v[30:31], v[36:37], v[34:35], v[30:31]
	s_or_b64 exec, exec, s[6:7]
	v_lshlrev_b32_e32 v32, 16, v50
	v_and_b32_e32 v33, 0xffff0000, v50
	v_pk_mul_f32 v[36:37], v[24:25], v[32:33]
	v_cvt_pk_bf16_f32 v40, v36, v37
	v_lshlrev_b32_e32 v32, 16, v51
	v_and_b32_e32 v33, 0xffff0000, v51
	v_pk_mul_f32 v[36:37], v[26:27], v[32:33]
	v_cvt_pk_bf16_f32 v41, v36, v37
	v_lshlrev_b32_e32 v32, 16, v52
	v_and_b32_e32 v33, 0xffff0000, v52
	v_pk_mul_f32 v[36:37], v[28:29], v[32:33]
	v_cvt_pk_bf16_f32 v42, v36, v37
	v_lshlrev_b32_e32 v32, 16, v53
	v_and_b32_e32 v33, 0xffff0000, v53
	v_pk_mul_f32 v[36:37], v[30:31], v[32:33]
	v_cvt_pk_bf16_f32 v43, v36, v37
	global_store_dwordx4 v[130:131], v[40:43], off
	s_waitcnt vmcnt(15)
; __device__ __forceinline__ size_t paddr(int row, int col) { return ((size_t)(col >> 7) * 16384 + (size_t)row) * 128 + (col & 127); }
; __device__ __forceinline__ size_t paddr(int row, int col) { return ((size_t)(col >> 7) * TH + (size_t)row) * 128 + (col & 127); }
; __device__ __forceinline__ unsigned pk2(float lo, float hi) { unsigned r; asm("v_cvt_pk_bf16_f32 %0, %1, %2" : "=v"(r) : "v"(lo), "v"(hi)); return r; }
; __device__ __forceinline__ void mixers_phase(const PP& p, int l, int hf, unsigned char* lds) {
;     ...
;             for (int k = 0; k < 16; ++k) {
;                 const int i = i0 + k * 512;
;                 const int row = i >> 7, c8 = (i & 127) * 8, t = row & (SEQ - 1);
;                 const bf16* src = proj + paddr(row, c8);
;                 constexpr size_t SEGS = (size_t)8 * TH * 128;
;                 float cb[8], a[8], bq[8], acc[8];
;                 unpk8(*(const u32x4*)(src), cb);
;                 unpk8(*(const u32x4*)(src + SEGS), a); unpk8(*(const u32x4*)(src + 2 * SEGS), bq);
;                 const f32x4 w2a = *(const f32x4*)(cw + 2048 + c8), w2b = *(const f32x4*)(cw + 2048 + c8 + 4);
; #pragma unroll
;                 for (int j = 0; j < 8; ++j) acc[j] = (j < 4 ? w2a[j] : w2b[j - 4]) * a[j] * bq[j];
;                 if (t >= 1) {
;                     unpk8(*(const u32x4*)(src - 128 + SEGS), a); unpk8(*(const u32x4*)(src - 128 + 2 * SEGS), bq);
;                     const f32x4 w1a = *(const f32x4*)(cw + 1024 + c8), w1b = *(const f32x4*)(cw + 1024 + c8 + 4);
; #pragma unroll
;                     for (int j = 0; j < 8; ++j) acc[j] += (j < 4 ? w1a[j] : w1b[j - 4]) * a[j] * bq[j];
;                 }
;                 if (t >= 2) {
;                     unpk8(*(const u32x4*)(src - 256 + SEGS), a); unpk8(*(const u32x4*)(src - 256 + 2 * SEGS), bq);
;                     const f32x4 w0a = *(const f32x4*)(cw + c8), w0b = *(const f32x4*)(cw + c8 + 4);
; #pragma unroll
;                     for (int j = 0; j < 8; ++j) acc[j] += (j < 4 ? w0a[j] : w0b[j - 4]) * a[j] * bq[j];
;                 }
;                 u32x4 o; o.x = pk2(cb[0] * acc[0], cb[1] * acc[1]); o.y = pk2(cb[2] * acc[2], cb[3] * acc[3]); o.z = pk2(cb[4] * acc[4], cb[5] * acc[5]); o.w = pk2(cb[6] * acc[6], cb[7] * acc[7]);
;                 *(u32x4*)(Y + (size_t)row * 1024 + c8) = o;
	v_lshlrev_b32_e32 v32, 16, v82
	v_and_b32_e32 v33, 0xffff0000, v82
	v_lshlrev_b32_e32 v34, 16, v86
	v_and_b32_e32 v35, 0xffff0000, v86
	v_pk_mul_f32 v[24:25], v[106:107], v[32:33]
	v_pk_mul_f32 v[24:25], v[24:25], v[34:35]
	v_lshlrev_b32_e32 v32, 16, v83
	v_and_b32_e32 v33, 0xffff0000, v83
	v_lshlrev_b32_e32 v34, 16, v87
	v_and_b32_e32 v35, 0xffff0000, v87
	v_pk_mul_f32 v[26:27], v[108:109], v[32:33]
	v_pk_mul_f32 v[26:27], v[26:27], v[34:35]
	v_lshlrev_b32_e32 v32, 16, v84
	v_and_b32_e32 v33, 0xffff0000, v84
	v_lshlrev_b32_e32 v34, 16, v88
	v_and_b32_e32 v35, 0xffff0000, v88
	v_pk_mul_f32 v[28:29], v[110:111], v[32:33]
	v_pk_mul_f32 v[28:29], v[28:29], v[34:35]
	v_lshlrev_b32_e32 v32, 16, v85
	v_and_b32_e32 v33, 0xffff0000, v85
	v_lshlrev_b32_e32 v34, 16, v89
	v_and_b32_e32 v35, 0xffff0000, v89
	v_pk_mul_f32 v[30:31], v[112:113], v[32:33]
	v_pk_mul_f32 v[30:31], v[30:31], v[34:35]
	v_cmp_ne_u32_e32 vcc, 0, v39
	s_and_saveexec_b64 s[6:7], vcc
	v_lshlrev_b32_e32 v32, 16, v90
	v_and_b32_e32 v33, 0xffff0000, v90
	v_lshlrev_b32_e32 v34, 16, v94
	v_and_b32_e32 v35, 0xffff0000, v94
	v_pk_mul_f32 v[36:37], v[114:115], v[32:33]
	v_pk_fma_f32 v[24:25], v[36:37], v[34:35], v[24:25]
	v_lshlrev_b32_e32 v32, 16, v91
	v_and_b32_e32 v33, 0xffff0000, v91
	v_lshlrev_b32_e32 v34, 16, v95
	v_and_b32_e32 v35, 0xffff0000, v95
	v_pk_mul_f32 v[36:37], v[116:117], v[32:33]
	v_pk_fma_f32 v[26:27], v[36:37], v[34:35], v[26:27]
	v_lshlrev_b32_e32 v32, 16, v92
	v_and_b32_e32 v33, 0xffff0000, v92
	v_lshlrev_b32_e32 v34, 16, v96
	v_and_b32_e32 v35, 0xffff0000, v96
	v_pk_mul_f32 v[36:37], v[118:119], v[32:33]
	v_pk_fma_f32 v[28:29], v[36:37], v[34:35], v[28:29]
	v_lshlrev_b32_e32 v32, 16, v93
	v_and_b32_e32 v33, 0xffff0000, v93
	v_lshlrev_b32_e32 v34, 16, v97
	v_and_b32_e32 v35, 0xffff0000, v97
	v_pk_mul_f32 v[36:37], v[120:121], v[32:33]
	v_pk_fma_f32 v[30:31], v[36:37], v[34:35], v[30:31]
	s_or_b64 exec, exec, s[6:7]
	v_cmp_lt_u32_e32 vcc, 1, v39
	s_and_saveexec_b64 s[6:7], vcc
	v_lshlrev_b32_e32 v32, 16, v98
	v_and_b32_e32 v33, 0xffff0000, v98
	v_lshlrev_b32_e32 v34, 16, v102
	v_and_b32_e32 v35, 0xffff0000, v102
	v_pk_mul_f32 v[36:37], v[122:123], v[32:33]
	v_pk_fma_f32 v[24:25], v[36:37], v[34:35], v[24:25]
	v_lshlrev_b32_e32 v32, 16, v99
	v_and_b32_e32 v33, 0xffff0000, v99
	v_lshlrev_b32_e32 v34, 16, v103
	v_and_b32_e32 v35, 0xffff0000, v103
	v_pk_mul_f32 v[36:37], v[124:125], v[32:33]
	v_pk_fma_f32 v[26:27], v[36:37], v[34:35], v[26:27]
	v_lshlrev_b32_e32 v32, 16, v100
	v_and_b32_e32 v33, 0xffff0000, v100
	v_lshlrev_b32_e32 v34, 16, v104
	v_and_b32_e32 v35, 0xffff0000, v104
	v_pk_mul_f32 v[36:37], v[126:127], v[32:33]
	v_pk_fma_f32 v[28:29], v[36:37], v[34:35], v[28:29]
	v_lshlrev_b32_e32 v32, 16, v101
	v_and_b32_e32 v33, 0xffff0000, v101
	v_lshlrev_b32_e32 v34, 16, v105
	v_and_b32_e32 v35, 0xffff0000, v105
	v_pk_mul_f32 v[36:37], v[128:129], v[32:33]
	v_pk_fma_f32 v[30:31], v[36:37], v[34:35], v[30:31]
	s_or_b64 exec, exec, s[6:7]
	v_lshlrev_b32_e32 v32, 16, v78
	v_and_b32_e32 v33, 0xffff0000, v78
	v_pk_mul_f32 v[36:37], v[24:25], v[32:33]
	v_cvt_pk_bf16_f32 v40, v36, v37
	v_lshlrev_b32_e32 v32, 16, v79
	v_and_b32_e32 v33, 0xffff0000, v79
	v_pk_mul_f32 v[36:37], v[26:27], v[32:33]
	v_cvt_pk_bf16_f32 v41, v36, v37
	v_lshlrev_b32_e32 v32, 16, v80
	v_and_b32_e32 v33, 0xffff0000, v80
	v_pk_mul_f32 v[36:37], v[28:29], v[32:33]
	v_cvt_pk_bf16_f32 v42, v36, v37
	v_lshlrev_b32_e32 v32, 16, v81
	v_and_b32_e32 v33, 0xffff0000, v81
	v_pk_mul_f32 v[36:37], v[30:31], v[32:33]
	v_cvt_pk_bf16_f32 v43, v36, v37
	global_store_dwordx4 v[132:133], v[40:43], off
	s_waitcnt vmcnt(9)
	v_lshlrev_b32_e32 v32, 16, v160
	v_and_b32_e32 v33, 0xffff0000, v160
	v_lshlrev_b32_e32 v34, 16, v164
	v_and_b32_e32 v35, 0xffff0000, v164
	v_pk_mul_f32 v[24:25], v[106:107], v[32:33]
	v_pk_mul_f32 v[24:25], v[24:25], v[34:35]
	v_lshlrev_b32_e32 v32, 16, v161
	v_and_b32_e32 v33, 0xffff0000, v161
	v_lshlrev_b32_e32 v34, 16, v165
	v_and_b32_e32 v35, 0xffff0000, v165
	v_pk_mul_f32 v[26:27], v[108:109], v[32:33]
	v_pk_mul_f32 v[26:27], v[26:27], v[34:35]
	v_lshlrev_b32_e32 v32, 16, v162
	v_and_b32_e32 v33, 0xffff0000, v162
	v_lshlrev_b32_e32 v34, 16, v166
	v_and_b32_e32 v35, 0xffff0000, v166
	v_pk_mul_f32 v[28:29], v[110:111], v[32:33]
	v_pk_mul_f32 v[28:29], v[28:29], v[34:35]
	v_lshlrev_b32_e32 v32, 16, v163
	v_and_b32_e32 v33, 0xffff0000, v163
	v_lshlrev_b32_e32 v34, 16, v167
	v_and_b32_e32 v35, 0xffff0000, v167
	v_pk_mul_f32 v[30:31], v[112:113], v[32:33]
	v_pk_mul_f32 v[30:31], v[30:31], v[34:35]
	v_cmp_ne_u32_e32 vcc, 0, v44
	s_and_saveexec_b64 s[6:7], vcc
	v_lshlrev_b32_e32 v32, 16, v168
	v_and_b32_e32 v33, 0xffff0000, v168
	v_lshlrev_b32_e32 v34, 16, v172
	v_and_b32_e32 v35, 0xffff0000, v172
	v_pk_mul_f32 v[36:37], v[114:115], v[32:33]
	v_pk_fma_f32 v[24:25], v[36:37], v[34:35], v[24:25]
	v_lshlrev_b32_e32 v32, 16, v169
	v_and_b32_e32 v33, 0xffff0000, v169
	v_lshlrev_b32_e32 v34, 16, v173
	v_and_b32_e32 v35, 0xffff0000, v173
	v_pk_mul_f32 v[36:37], v[116:117], v[32:33]
	v_pk_fma_f32 v[26:27], v[36:37], v[34:35], v[26:27]
	v_lshlrev_b32_e32 v32, 16, v170
	v_and_b32_e32 v33, 0xffff0000, v170
	v_lshlrev_b32_e32 v34, 16, v174
	v_and_b32_e32 v35, 0xffff0000, v174
	v_pk_mul_f32 v[36:37], v[118:119], v[32:33]
	v_pk_fma_f32 v[28:29], v[36:37], v[34:35], v[28:29]
	v_lshlrev_b32_e32 v32, 16, v171
	v_and_b32_e32 v33, 0xffff0000, v171
	v_lshlrev_b32_e32 v34, 16, v175
	v_and_b32_e32 v35, 0xffff0000, v175
	v_pk_mul_f32 v[36:37], v[120:121], v[32:33]
; __device__ __forceinline__ size_t paddr(int row, int col) { return ((size_t)(col >> 7) * 16384 + (size_t)row) * 128 + (col & 127); }
; __device__ __forceinline__ size_t paddr(int row, int col) { return ((size_t)(col >> 7) * TH + (size_t)row) * 128 + (col & 127); }
; __device__ __forceinline__ unsigned pk2(float lo, float hi) { unsigned r; asm("v_cvt_pk_bf16_f32 %0, %1, %2" : "=v"(r) : "v"(lo), "v"(hi)); return r; }
; __device__ __forceinline__ void mixers_phase(const PP& p, int l, int hf, unsigned char* lds) {
;     ...
;             for (int k = 0; k < 16; ++k) {
;                 const int i = i0 + k * 512;
;                 const int row = i >> 7, c8 = (i & 127) * 8, t = row & (SEQ - 1);
;                 const bf16* src = proj + paddr(row, c8);
;                 constexpr size_t SEGS = (size_t)8 * TH * 128;
;                 float cb[8], a[8], bq[8], acc[8];
;                 unpk8(*(const u32x4*)(src), cb);
;                 unpk8(*(const u32x4*)(src + SEGS), a); unpk8(*(const u32x4*)(src + 2 * SEGS), bq);
;                 const f32x4 w2a = *(const f32x4*)(cw + 2048 + c8), w2b = *(const f32x4*)(cw + 2048 + c8 + 4);
; #pragma unroll
;                 for (int j = 0; j < 8; ++j) acc[j] = (j < 4 ? w2a[j] : w2b[j - 4]) * a[j] * bq[j];
;                 if (t >= 1) {
;                     unpk8(*(const u32x4*)(src - 128 + SEGS), a); unpk8(*(const u32x4*)(src - 128 + 2 * SEGS), bq);
;                     const f32x4 w1a = *(const f32x4*)(cw + 1024 + c8), w1b = *(const f32x4*)(cw + 1024 + c8 + 4);
; #pragma unroll
;                     for (int j = 0; j < 8; ++j) acc[j] += (j < 4 ? w1a[j] : w1b[j - 4]) * a[j] * bq[j];
;                 }
;                 if (t >= 2) {
;                     unpk8(*(const u32x4*)(src - 256 + SEGS), a); unpk8(*(const u32x4*)(src - 256 + 2 * SEGS), bq);
;                     const f32x4 w0a = *(const f32x4*)(cw + c8), w0b = *(const f32x4*)(cw + c8 + 4);
; #pragma unroll
;                     for (int j = 0; j < 8; ++j) acc[j] += (j < 4 ? w0a[j] : w0b[j - 4]) * a[j] * bq[j];
;                 }
;                 u32x4 o; o.x = pk2(cb[0] * acc[0], cb[1] * acc[1]); o.y = pk2(cb[2] * acc[2], cb[3] * acc[3]); o.z = pk2(cb[4] * acc[4], cb[5] * acc[5]); o.w = pk2(cb[6] * acc[6], cb[7] * acc[7]);
;                 *(u32x4*)(Y + (size_t)row * 1024 + c8) = o;
;             }
	v_pk_fma_f32 v[30:31], v[36:37], v[34:35], v[30:31]
	s_or_b64 exec, exec, s[6:7]
	v_cmp_lt_u32_e32 vcc, 1, v44
	s_and_saveexec_b64 s[6:7], vcc
	v_lshlrev_b32_e32 v32, 16, v176
	v_and_b32_e32 v33, 0xffff0000, v176
	v_lshlrev_b32_e32 v34, 16, v180
	v_and_b32_e32 v35, 0xffff0000, v180
	v_pk_mul_f32 v[36:37], v[122:123], v[32:33]
	v_pk_fma_f32 v[24:25], v[36:37], v[34:35], v[24:25]
	v_lshlrev_b32_e32 v32, 16, v177
	v_and_b32_e32 v33, 0xffff0000, v177
	v_lshlrev_b32_e32 v34, 16, v181
	v_and_b32_e32 v35, 0xffff0000, v181
	v_pk_mul_f32 v[36:37], v[124:125], v[32:33]
	v_pk_fma_f32 v[26:27], v[36:37], v[34:35], v[26:27]
	v_lshlrev_b32_e32 v32, 16, v178
	v_and_b32_e32 v33, 0xffff0000, v178
	v_lshlrev_b32_e32 v34, 16, v182
	v_and_b32_e32 v35, 0xffff0000, v182
	v_pk_mul_f32 v[36:37], v[126:127], v[32:33]
	v_pk_fma_f32 v[28:29], v[36:37], v[34:35], v[28:29]
	v_lshlrev_b32_e32 v32, 16, v179
	v_and_b32_e32 v33, 0xffff0000, v179
	v_lshlrev_b32_e32 v34, 16, v183
	v_and_b32_e32 v35, 0xffff0000, v183
	v_pk_mul_f32 v[36:37], v[128:129], v[32:33]
	v_pk_fma_f32 v[30:31], v[36:37], v[34:35], v[30:31]
	s_or_b64 exec, exec, s[6:7]
	v_lshlrev_b32_e32 v32, 16, v156
	v_and_b32_e32 v33, 0xffff0000, v156
	v_pk_mul_f32 v[36:37], v[24:25], v[32:33]
	v_cvt_pk_bf16_f32 v40, v36, v37
	v_lshlrev_b32_e32 v32, 16, v157
	v_and_b32_e32 v33, 0xffff0000, v157
	v_pk_mul_f32 v[36:37], v[26:27], v[32:33]
	v_cvt_pk_bf16_f32 v41, v36, v37
	v_lshlrev_b32_e32 v32, 16, v158
	v_and_b32_e32 v33, 0xffff0000, v158
	v_pk_mul_f32 v[36:37], v[28:29], v[32:33]
	v_cvt_pk_bf16_f32 v42, v36, v37
	v_lshlrev_b32_e32 v32, 16, v159
	v_and_b32_e32 v33, 0xffff0000, v159
	v_pk_mul_f32 v[36:37], v[30:31], v[32:33]
	v_cvt_pk_bf16_f32 v43, v36, v37
	global_store_dwordx4 v[134:135], v[40:43], off
	s_waitcnt vmcnt(3)
	v_lshlrev_b32_e32 v32, 16, v198
	v_and_b32_e32 v33, 0xffff0000, v198
	v_lshlrev_b32_e32 v34, 16, v202
	v_and_b32_e32 v35, 0xffff0000, v202
	v_pk_mul_f32 v[24:25], v[106:107], v[32:33]
	v_pk_mul_f32 v[24:25], v[24:25], v[34:35]
	v_lshlrev_b32_e32 v32, 16, v199
	v_and_b32_e32 v33, 0xffff0000, v199
	v_lshlrev_b32_e32 v34, 16, v203
	v_and_b32_e32 v35, 0xffff0000, v203
	v_pk_mul_f32 v[26:27], v[108:109], v[32:33]
	v_pk_mul_f32 v[26:27], v[26:27], v[34:35]
	v_lshlrev_b32_e32 v32, 16, v200
	v_and_b32_e32 v33, 0xffff0000, v200
	v_lshlrev_b32_e32 v34, 16, v204
	v_and_b32_e32 v35, 0xffff0000, v204
	v_pk_mul_f32 v[28:29], v[110:111], v[32:33]
	v_pk_mul_f32 v[28:29], v[28:29], v[34:35]
	v_lshlrev_b32_e32 v32, 16, v201
	v_and_b32_e32 v33, 0xffff0000, v201
	v_lshlrev_b32_e32 v34, 16, v205
	v_and_b32_e32 v35, 0xffff0000, v205
	v_pk_mul_f32 v[30:31], v[112:113], v[32:33]
	v_pk_mul_f32 v[30:31], v[30:31], v[34:35]
	v_cmp_ne_u32_e32 vcc, 0, v45
	s_and_saveexec_b64 s[6:7], vcc
	v_lshlrev_b32_e32 v32, 16, v206
	v_and_b32_e32 v33, 0xffff0000, v206
	v_lshlrev_b32_e32 v34, 16, v210
	v_and_b32_e32 v35, 0xffff0000, v210
	v_pk_mul_f32 v[36:37], v[114:115], v[32:33]
	v_pk_fma_f32 v[24:25], v[36:37], v[34:35], v[24:25]
	v_lshlrev_b32_e32 v32, 16, v207
	v_and_b32_e32 v33, 0xffff0000, v207
	v_lshlrev_b32_e32 v34, 16, v211
	v_and_b32_e32 v35, 0xffff0000, v211
	v_pk_mul_f32 v[36:37], v[116:117], v[32:33]
	v_pk_fma_f32 v[26:27], v[36:37], v[34:35], v[26:27]
	v_lshlrev_b32_e32 v32, 16, v208
	v_and_b32_e32 v33, 0xffff0000, v208
	v_lshlrev_b32_e32 v34, 16, v212
	v_and_b32_e32 v35, 0xffff0000, v212
	v_pk_mul_f32 v[36:37], v[118:119], v[32:33]
	v_pk_fma_f32 v[28:29], v[36:37], v[34:35], v[28:29]
	v_lshlrev_b32_e32 v32, 16, v209
	v_and_b32_e32 v33, 0xffff0000, v209
	v_lshlrev_b32_e32 v34, 16, v213
	v_and_b32_e32 v35, 0xffff0000, v213
	v_pk_mul_f32 v[36:37], v[120:121], v[32:33]
	v_pk_fma_f32 v[30:31], v[36:37], v[34:35], v[30:31]
	s_or_b64 exec, exec, s[6:7]
	v_cmp_lt_u32_e32 vcc, 1, v45
	s_and_saveexec_b64 s[6:7], vcc
	v_lshlrev_b32_e32 v32, 16, v214
	v_and_b32_e32 v33, 0xffff0000, v214
	v_lshlrev_b32_e32 v34, 16, v218
	v_and_b32_e32 v35, 0xffff0000, v218
	v_pk_mul_f32 v[36:37], v[122:123], v[32:33]
	v_pk_fma_f32 v[24:25], v[36:37], v[34:35], v[24:25]
	v_lshlrev_b32_e32 v32, 16, v215
	v_and_b32_e32 v33, 0xffff0000, v215
	v_lshlrev_b32_e32 v34, 16, v219
	v_and_b32_e32 v35, 0xffff0000, v219
	v_pk_mul_f32 v[36:37], v[124:125], v[32:33]
	v_pk_fma_f32 v[26:27], v[36:37], v[34:35], v[26:27]
	v_lshlrev_b32_e32 v32, 16, v216
	v_and_b32_e32 v33, 0xffff0000, v216
	v_lshlrev_b32_e32 v34, 16, v220
	v_and_b32_e32 v35, 0xffff0000, v220
	v_pk_mul_f32 v[36:37], v[126:127], v[32:33]
	v_pk_fma_f32 v[28:29], v[36:37], v[34:35], v[28:29]
	v_lshlrev_b32_e32 v32, 16, v217
	v_and_b32_e32 v33, 0xffff0000, v217
	v_lshlrev_b32_e32 v34, 16, v221
	v_and_b32_e32 v35, 0xffff0000, v221
	v_pk_mul_f32 v[36:37], v[128:129], v[32:33]
	v_pk_fma_f32 v[30:31], v[36:37], v[34:35], v[30:31]
	s_or_b64 exec, exec, s[6:7]
	v_lshlrev_b32_e32 v32, 16, v184
	v_and_b32_e32 v33, 0xffff0000, v184
	v_pk_mul_f32 v[36:37], v[24:25], v[32:33]
	v_cvt_pk_bf16_f32 v40, v36, v37
	v_lshlrev_b32_e32 v32, 16, v185
	v_and_b32_e32 v33, 0xffff0000, v185
	v_pk_mul_f32 v[36:37], v[26:27], v[32:33]
	v_cvt_pk_bf16_f32 v41, v36, v37
	v_lshlrev_b32_e32 v32, 16, v186
	v_and_b32_e32 v33, 0xffff0000, v186
	v_pk_mul_f32 v[36:37], v[28:29], v[32:33]
	v_cvt_pk_bf16_f32 v42, v36, v37
	v_lshlrev_b32_e32 v32, 16, v187
	v_and_b32_e32 v33, 0xffff0000, v187
	v_pk_mul_f32 v[36:37], v[30:31], v[32:33]
	v_cvt_pk_bf16_f32 v43, v36, v37
	global_store_dwordx4 v[136:137], v[40:43], off
	s_addk_i32 s2, 0x800
	s_cmp_eq_u32 s2, 0
	s_cbranch_scc0 .LBB0_270
